# LayerNorm wave sums via DPP row-shift/row-broadcast adds + readlane broadcast instead of 12 serialized ds_bpermute round trips per row
# baseline (speedup 1.0000x reference)
;   __device__ __forceinline__ const float* x() const { return (const float*)(const __attribute__((address_space(1))) float*)kp[0]; }
;   __device__ __forceinline__ const float* ln_g() const { return (const float*)(const __attribute__((address_space(1))) float*)kp[16]; }
;   __device__ __forceinline__ const float* ln_b() const { return (const float*)(const __attribute__((address_space(1))) float*)kp[17]; }
;   __device__ __forceinline__ float* out() const { return (float*)(__attribute__((address_space(1))) float*)kp[18]; }
; __device__ __forceinline__ void ln_rows(const KP& p, int lprev, bool final_) {
;     ...
;   for (int row = gw; row < NTOK; row += nw) {
;     const float4* rp = (const float4*)((lprev < 0 ? p.x() : (const float*)p.u()) + (size_t)row * DM);
;     float4 v[4];
;     float s = 0.f;
; #pragma unroll
;     for (int i = 0; i < 4; ++i) {
;       v[i] = rp[lane + 64 * i];
;       s += v[i].x + v[i].y + v[i].z + v[i].w;
;     }
;     if (lprev >= 0) {
;       float mu = wave_sum(s) * (1.f / DM);
;       float q = 0.f;
; #pragma unroll
;       for (int i = 0; i < 4; ++i) {
;         float a = v[i].x - mu, b = v[i].y - mu, c = v[i].z - mu, d = v[i].w - mu;
;         q += a * a + b * b + c * c + d * d;
;       }
;       float rstd = rsqrtf(wave_sum(q) * (1.f / DM) + 1e-5f);
;       const float4* g4 = (const float4*)(p.ln_g() + lprev * DM);
;       const float4* b4 = (const float4*)(p.ln_b() + lprev * DM);
; #pragma unroll
;       for (int i = 0; i < 4; ++i) {
;         float4 g = g4[lane + 64 * i], bb = b4[lane + 64 * i];
;         v[i].x = (v[i].x - mu) * rstd * g.x + bb.x;
;         v[i].y = (v[i].y - mu) * rstd * g.y + bb.y;
;         v[i].z = (v[i].z - mu) * rstd * g.z + bb.z;
;         v[i].w = (v[i].w - mu) * rstd * g.w + bb.w;
;       }
;     }
;     if (final_) {
;       float4* op = (float4*)(p.out() + (size_t)row * DM);
; #pragma unroll
;       for (int i = 0; i < 4; ++i) op[lane + 64 * i] = v[i];
;     } else {
;       float4* op = (float4*)(p.xr() + (size_t)row * DM);
;       h4* hp = (h4*)(p.xh() + (size_t)row * DM);
; #pragma unroll
;       for (int i = 0; i < 4; ++i) {
;         op[lane + 64 * i] = v[i];
;         h4 hv;
;         hv[0] = (half_t)v[i].x; hv[1] = (half_t)v[i].y; hv[2] = (half_t)v[i].z; hv[3] = (half_t)v[i].w;
;         hp[lane + 64 * i] = hv;
;       }
;     }
;   }
.LBB0_1870:
	v_lshl_add_u32 v76, v2, 6, v77
	v_lshl_add_u64 v[66:67], s[16:17], 0, v[10:11]
	v_add_co_u32_e32 v54, vcc, 0x6000000, v66
	v_lshl_add_u64 v[68:69], s[16:17], 0, v[8:9]
	s_nop 0
	v_addc_co_u32_e32 v55, vcc, 0, v67, vcc
	global_load_dwordx4 v[18:21], v[54:55], off
	global_load_dwordx4 v[22:25], v[4:5], off
	global_load_dwordx4 v[26:29], v[6:7], off
	global_load_dwordx4 v[30:33], v[54:55], off offset:1024
	global_load_dwordx4 v[34:37], v[4:5], off offset:1024
	global_load_dwordx4 v[38:41], v[6:7], off offset:1024
	v_add_u32_e32 v2, s48, v2
	v_lshl_add_u64 v[8:9], v[8:9], 0, s[70:71]
	v_lshl_add_u64 v[10:11], v[10:11], 0, s[78:79]
	s_waitcnt vmcnt(5)
	v_mov_b32_e32 v42, v18
	s_waitcnt vmcnt(2)
	v_mov_b32_e32 v43, v30
	v_mov_b32_e32 v44, v19
	v_mov_b32_e32 v45, v31
	v_pk_add_f32 v[42:43], v[42:43], v[44:45]
	v_mov_b32_e32 v44, v20
	v_mov_b32_e32 v45, v32
	v_pk_add_f32 v[42:43], v[42:43], v[44:45]
	v_mov_b32_e32 v44, v21
	v_mov_b32_e32 v45, v33
	v_pk_add_f32 v[42:43], v[42:43], v[44:45]
	s_nop 0
	v_add_f32_e32 v0, 0, v42
	v_add_f32_e32 v0, v0, v43
	global_load_dwordx4 v[42:45], v[54:55], off offset:2048
	global_load_dwordx4 v[46:49], v[4:5], off offset:2048
	global_load_dwordx4 v[50:53], v[6:7], off offset:2048
	s_nop 0
	global_load_dwordx4 v[54:57], v[54:55], off offset:3072
	s_nop 0
	global_load_dwordx4 v[58:61], v[4:5], off offset:3072
	global_load_dwordx4 v[62:65], v[6:7], off offset:3072
	s_waitcnt vmcnt(5)
	v_mov_b32_e32 v70, v42
	v_mov_b32_e32 v72, v43
	s_waitcnt vmcnt(2)
	v_mov_b32_e32 v71, v54
	v_mov_b32_e32 v73, v55
	v_pk_add_f32 v[70:71], v[70:71], v[72:73]
	v_mov_b32_e32 v72, v44
	v_mov_b32_e32 v73, v56
	v_pk_add_f32 v[70:71], v[70:71], v[72:73]
	v_mov_b32_e32 v72, v45
	v_mov_b32_e32 v73, v57
	v_pk_add_f32 v[70:71], v[70:71], v[72:73]
	s_nop 0
	v_add_f32_e32 v0, v0, v70
	v_add_f32_e32 v0, v0, v71
	s_nop 1
	v_add_f32_dpp v0, v0, v0 row_shr:1 row_mask:0xf bank_mask:0xf
	s_nop 1
	v_add_f32_dpp v0, v0, v0 row_shr:2 row_mask:0xf bank_mask:0xf
	s_nop 1
	v_add_f32_dpp v0, v0, v0 row_shr:4 row_mask:0xf bank_mask:0xf
	s_nop 1
	v_add_f32_dpp v0, v0, v0 row_shr:8 row_mask:0xf bank_mask:0xf
	s_nop 1
	v_add_f32_dpp v0, v0, v0 row_bcast:15 row_mask:0xa bank_mask:0xf
	s_nop 1
	v_add_f32_dpp v0, v0, v0 row_bcast:31 row_mask:0xc bank_mask:0xf
	s_nop 1
	v_readlane_b32 s2, v0, 63
	s_nop 2
	v_mov_b32_e32 v0, s2
	v_mul_f32_e32 v0, 0x3a800000, v0
	v_pk_add_f32 v[18:19], v[18:19], v[0:1] op_sel_hi:[1,0] neg_lo:[0,1] neg_hi:[0,1]
	v_pk_add_f32 v[30:31], v[30:31], v[0:1] op_sel_hi:[1,0] neg_lo:[0,1] neg_hi:[0,1]
	v_mov_b32_e32 v72, v19
	v_mov_b32_e32 v73, v31
	v_pk_add_f32 v[20:21], v[20:21], v[0:1] op_sel_hi:[1,0] neg_lo:[0,1] neg_hi:[0,1]
	v_pk_add_f32 v[32:33], v[32:33], v[0:1] op_sel_hi:[1,0] neg_lo:[0,1] neg_hi:[0,1]
	v_mov_b32_e32 v70, v18
	v_mov_b32_e32 v71, v30
	v_pk_mul_f32 v[72:73], v[72:73], v[72:73]
	v_pk_add_f32 v[42:43], v[42:43], v[0:1] op_sel_hi:[1,0] neg_lo:[0,1] neg_hi:[0,1]
	v_pk_fma_f32 v[70:71], v[70:71], v[70:71], v[72:73]
	v_mov_b32_e32 v72, v20
	v_mov_b32_e32 v73, v32
	v_pk_add_f32 v[54:55], v[54:55], v[0:1] op_sel_hi:[1,0] neg_lo:[0,1] neg_hi:[0,1]
	v_pk_fma_f32 v[70:71], v[72:73], v[72:73], v[70:71]
	v_mov_b32_e32 v72, v21
	v_mov_b32_e32 v73, v33
	v_mov_b32_e32 v74, v55
	v_mov_b32_e32 v75, v43
	v_pk_fma_f32 v[70:71], v[72:73], v[72:73], v[70:71]
	v_pk_add_f32 v[44:45], v[44:45], v[0:1] op_sel_hi:[1,0] neg_lo:[0,1] neg_hi:[0,1]
	v_pk_add_f32 v[56:57], v[56:57], v[0:1] op_sel_hi:[1,0] neg_lo:[0,1] neg_hi:[0,1]
	v_mov_b32_e32 v72, v54
	v_mov_b32_e32 v73, v42
	v_pk_mul_f32 v[74:75], v[74:75], v[74:75]
	v_add_f32_e32 v0, v70, v71
	v_pk_fma_f32 v[72:73], v[72:73], v[72:73], v[74:75]
	v_mov_b32_e32 v74, v56
	v_mov_b32_e32 v75, v44
	v_pk_fma_f32 v[72:73], v[74:75], v[74:75], v[72:73]
	v_mov_b32_e32 v74, v57
	v_mov_b32_e32 v75, v45
	v_pk_fma_f32 v[72:73], v[74:75], v[74:75], v[72:73]
	s_nop 0
	v_add_f32_e32 v0, v73, v0
	v_add_f32_e32 v0, v72, v0
	s_nop 1
	v_add_f32_dpp v0, v0, v0 row_shr:1 row_mask:0xf bank_mask:0xf
	s_nop 1
	v_add_f32_dpp v0, v0, v0 row_shr:2 row_mask:0xf bank_mask:0xf
	s_nop 1
	v_add_f32_dpp v0, v0, v0 row_shr:4 row_mask:0xf bank_mask:0xf
	s_nop 1
	v_add_f32_dpp v0, v0, v0 row_shr:8 row_mask:0xf bank_mask:0xf
	s_nop 1
	v_add_f32_dpp v0, v0, v0 row_bcast:15 row_mask:0xa bank_mask:0xf
	s_nop 1
	v_add_f32_dpp v0, v0, v0 row_bcast:31 row_mask:0xc bank_mask:0xf
	s_nop 1
	v_readlane_b32 s2, v0, 63
	s_nop 2
	v_mov_b32_e32 v0, s2
	v_fmamk_f32 v0, v0, 0x3a800000, v231
	v_cmp_gt_f32_e32 vcc, s66, v0
	v_mul_f32_e32 v3, 0x4b800000, v0
	s_nop 0
	v_cndmask_b32_e32 v0, v0, v3, vcc
	v_rsq_f32_e32 v0, v0
	s_nop 0
	v_mul_f32_e32 v3, 0x45800000, v0
	v_cndmask_b32_e32 v0, v0, v3, vcc
	v_pk_mul_f32 v[18:19], v[18:19], v[0:1] op_sel_hi:[1,0]
	v_pk_mul_f32 v[20:21], v[20:21], v[0:1] op_sel_hi:[1,0]
	v_pk_fma_f32 v[18:19], v[22:23], v[18:19], v[26:27]
	v_pk_fma_f32 v[20:21], v[24:25], v[20:21], v[28:29]
	v_pk_mul_f32 v[22:23], v[30:31], v[0:1] op_sel_hi:[1,0]
	v_pk_mul_f32 v[24:25], v[32:33], v[0:1] op_sel_hi:[1,0]
	global_store_dwordx4 v[66:67], v[18:21], off
	v_pk_fma_f32 v[22:23], v[34:35], v[22:23], v[38:39]
	v_pk_fma_f32 v[24:25], v[36:37], v[24:25], v[40:41]
	v_cvt_pk_f16_f32 v21, v20, v21
	v_cvt_pk_f16_f32 v20, v18, v19
	v_add_co_u32_e32 v18, vcc, s4, v68
	v_pk_mul_f32 v[26:27], v[42:43], v[0:1] op_sel_hi:[1,0]
	v_pk_mul_f32 v[28:29], v[44:45], v[0:1] op_sel_hi:[1,0]
	v_addc_co_u32_e32 v19, vcc, 0, v69, vcc
	v_pk_fma_f32 v[26:27], v[46:47], v[26:27], v[50:51]
	v_pk_fma_f32 v[28:29], v[28:29], v[48:49], v[52:53]
	v_pk_mul_f32 v[30:31], v[54:55], v[0:1] op_sel_hi:[1,0]
	v_pk_mul_f32 v[32:33], v[56:57], v[0:1] op_sel_hi:[1,0]
	global_store_dwordx2 v76, v[20:21], s[16:17]
	global_store_dwordx4 v[66:67], v[22:25], off offset:1024
	v_cvt_pk_f16_f32 v21, v24, v25
	v_cvt_pk_f16_f32 v20, v22, v23
	s_waitcnt vmcnt(3)
	v_pk_fma_f32 v[30:31], v[30:31], v[58:59], v[62:63]
	v_pk_fma_f32 v[32:33], v[32:33], v[60:61], v[64:65]
	v_add_u32_e32 v78, 0x800000, v76
	global_store_dwordx2 v78, v[20:21], s[16:17]
	global_store_dwordx4 v[66:67], v[26:29], off offset:2048
	v_cvt_pk_f16_f32 v21, v28, v29
	v_cvt_pk_f16_f32 v20, v26, v27
	v_cmp_lt_i32_e32 vcc, s67, v2
	v_add_u32_e32 v79, 0x1000000, v76
	global_store_dwordx2 v79, v[20:21], s[16:17]
	global_store_dwordx4 v[66:67], v[30:33], off offset:3072
	v_cvt_pk_f16_f32 v21, v32, v33
	v_cvt_pk_f16_f32 v20, v30, v31
	s_or_b64 s[18:19], vcc, s[18:19]
	v_add_u32_e32 v80, 0x1800000, v76
	global_store_dwordx2 v80, v[20:21], s[16:17]
	s_andn2_b64 exec, exec, s[18:19]
	s_cbranch_execnz .LBB0_1870
